# final_norm_rows: gain vectors loaded once outside the row loop; next row prefetched across iterations (no per-store full waits)
# speedup vs baseline: 1.0115x; 1.0042x over previous
; __device__ __forceinline__ float bflo(unsigned w) { return __uint_as_float(w << 16); }
; __device__ __forceinline__ float bfhi(unsigned w) { return __uint_as_float(w & 0xffff0000u); }
; __device__ __forceinline__ void final_norm_rows(const bf16_t* xb, float* outf, const float* gain, int tid, int bid, int nbk) {
;     const int lane = tid & 63, wv = tid >> 6;
;     const int gw = bid * 8 + wv, NGW = nbk * 8;
;     for (int m = gw; m < MTOK; m += NGW) {
;         const bf16_t* xr = xb + (size_t)m * DM + lane * 8;
;         const u32x4 a = *(const u32x4*)xr, b = *(const u32x4*)(xr + 512);
;         float v[16];
;         v[0] = bflo(a.x); v[1] = bfhi(a.x); v[2] = bflo(a.y); v[3] = bfhi(a.y); v[4] = bflo(a.z); v[5] = bfhi(a.z); v[6] = bflo(a.w); v[7] = bfhi(a.w);
;         v[8] = bflo(b.x); v[9] = bfhi(b.x); v[10] = bflo(b.y); v[11] = bfhi(b.y); v[12] = bflo(b.z); v[13] = bfhi(b.z); v[14] = bflo(b.w); v[15] = bfhi(b.w);
;         float s = 0.f;
; #pragma unroll
;         for (int i = 0; i < 16; ++i) s += v[i] * v[i];
;         const float r = 1.0f / sqrtf(wave_sum(s) * (1.f / DM) + 1e-6f);
;         float* o = outf + (size_t)m * DM + lane * 8; const float* g = gain + lane * 8;
; #pragma unroll
;         for (int hh = 0; hh < 2; ++hh)
; #pragma unroll
;             for (int q = 0; q < 2; ++q) { const f32x4 gg = *(const f32x4*)(g + hh * 512 + q * 4); f32x4 ov; ov[0] = v[hh * 8 + q * 4 + 0] * r * gg[0]; ov[1] = v[hh * 8 + q * 4 + 1] * r * gg[1]; ov[2] = v[hh * 8 + q * 4 + 2] * r * gg[2]; ov[3] = v[hh * 8 + q * 4 + 3] * r * gg[3]; *(f32x4*)(o + hh * 512 + q * 4) = ov; }
;     }
.LBB0_545:
	v_ashrrev_i32_e32 v4, 6, v187
	s_lshl_b32 s46, s11, 3
	v_add_u32_e32 v3, s46, v4
	s_mov_b32 s11, 0x8000
	v_cmp_gt_i32_e32 vcc, s11, v3
	s_and_saveexec_b64 s[12:13], vcc
	s_cbranch_execz .LBB0_548
	v_and_b32_e32 v0, 64, v178
	v_add_u32_e32 v0, 64, v0
	v_xor_b32_e32 v1, 1, v178
	v_cmp_lt_i32_e32 vcc, v1, v0
	s_load_dwordx4 s[40:43], s[0:1], 0xb0
	v_ashrrev_i32_e32 v5, 31, v4
	v_cndmask_b32_e32 v1, v178, v1, vcc
	s_waitcnt vmcnt(9)
	v_lshlrev_b32_e32 v8, 2, v1
	v_xor_b32_e32 v1, 2, v178
	v_cmp_lt_i32_e32 vcc, v1, v0
	s_ashr_i32 s47, s46, 31
	v_lshl_add_u64 v[6:7], v[4:5], 0, s[46:47]
	v_cndmask_b32_e32 v1, v178, v1, vcc
	v_lshlrev_b32_e32 v9, 2, v1
	v_xor_b32_e32 v1, 4, v178
	v_cmp_lt_i32_e32 vcc, v1, v0
	s_lshl_b32 s44, s10, 3
	v_lshlrev_b64 v[4:5], 11, v[6:7]
	v_cndmask_b32_e32 v1, v178, v1, vcc
	v_lshlrev_b32_e32 v10, 2, v1
	v_xor_b32_e32 v1, 8, v178
	v_cmp_lt_i32_e32 vcc, v1, v0
	s_waitcnt vmcnt(8)
	v_and_b32_e32 v14, 63, v187
	v_lshlrev_b64 v[6:7], 12, v[6:7]
	v_cndmask_b32_e32 v1, v178, v1, vcc
	v_lshlrev_b32_e32 v11, 2, v1
	v_xor_b32_e32 v1, 16, v178
	v_cmp_lt_i32_e32 vcc, v1, v0
	v_lshl_or_b32 v4, v14, 4, v4
	s_ashr_i32 s45, s44, 31
	v_cndmask_b32_e32 v1, v178, v1, vcc
	v_lshlrev_b32_e32 v12, 2, v1
	v_xor_b32_e32 v1, 32, v178
	v_cmp_lt_i32_e32 vcc, v1, v0
	v_lshl_or_b32 v6, v14, 5, v6
	v_lshl_add_u64 v[4:5], s[38:39], 0, v[4:5]
	v_cndmask_b32_e32 v0, v178, v1, vcc
	v_lshlrev_b32_e32 v13, 2, v0
	v_lshlrev_b32_e32 v0, 5, v187
	v_and_b32_e32 v0, 0x7e0, v0
	v_mov_b32_e32 v1, v2
	s_waitcnt lgkmcnt(0)
	v_lshl_add_u64 v[0:1], s[40:41], 0, v[0:1]
	s_lshl_b64 s[0:1], s[44:45], 11
	v_lshl_add_u64 v[6:7], s[42:43], 0, v[6:7]
	s_lshl_b64 s[38:39], s[44:45], 12
	s_mov_b64 s[42:43], 0
	global_load_dwordx4 v[188:191], v[0:1], off
	global_load_dwordx4 v[192:195], v[0:1], off offset:16
	global_load_dwordx4 v[196:199], v[0:1], off offset:2048
	global_load_dwordx4 v[200:203], v[0:1], off offset:2064
	global_load_dwordx4 v[204:207], v[4:5], off
	global_load_dwordx4 v[208:211], v[4:5], off offset:1024
	s_waitcnt vmcnt(0)
.LBB0_547:
	s_waitcnt vmcnt(4)
	v_mov_b32_e32 v14, v204
	v_mov_b32_e32 v15, v205
	v_mov_b32_e32 v16, v206
	v_mov_b32_e32 v17, v207
	v_mov_b32_e32 v18, v208
	v_mov_b32_e32 v19, v209
	v_mov_b32_e32 v20, v210
	v_mov_b32_e32 v21, v211
	v_mov_b32_e32 v22, v188
	v_mov_b32_e32 v23, v189
	v_mov_b32_e32 v24, v190
	v_mov_b32_e32 v25, v191
	v_add_u32_e32 v3, s44, v3
	v_lshl_add_u64 v[4:5], v[4:5], 0, s[0:1]
	global_load_dwordx4 v[204:207], v[4:5], off
	global_load_dwordx4 v[208:211], v[4:5], off offset:1024
	v_lshlrev_b32_e32 v28, 16, v14
	v_and_b32_e32 v29, 0xffff0000, v14
	v_and_b32_e32 v26, 0xffff0000, v21
	v_lshlrev_b32_e32 v27, 16, v21
	v_lshlrev_b32_e32 v14, 16, v15
	v_and_b32_e32 v15, 0xffff0000, v15
	v_lshlrev_b32_e32 v36, 16, v20
	v_and_b32_e32 v37, 0xffff0000, v20
	v_pk_mul_f32 v[20:21], v[28:29], v[28:29]
	v_pk_mul_f32 v[38:39], v[14:15], v[14:15]
	v_add_f32_e32 v20, v20, v21
	v_lshlrev_b32_e32 v30, 16, v16
	v_and_b32_e32 v31, 0xffff0000, v16
	v_add_f32_e32 v20, v38, v20
	v_pk_mul_f32 v[40:41], v[30:31], v[30:31]
	v_add_f32_e32 v20, v39, v20
	v_lshlrev_b32_e32 v32, 16, v17
	v_and_b32_e32 v33, 0xffff0000, v17
	v_add_f32_e32 v20, v40, v20
	v_pk_mul_f32 v[42:43], v[32:33], v[32:33]
	v_add_f32_e32 v20, v41, v20
	v_lshlrev_b32_e32 v34, 16, v18
	v_and_b32_e32 v35, 0xffff0000, v18
	v_add_f32_e32 v20, v42, v20
	v_pk_mul_f32 v[44:45], v[34:35], v[34:35]
	v_add_f32_e32 v20, v43, v20
	v_lshlrev_b32_e32 v18, 16, v19
	v_and_b32_e32 v19, 0xffff0000, v19
	v_add_f32_e32 v20, v44, v20
	v_pk_mul_f32 v[46:47], v[18:19], v[18:19]
	v_add_f32_e32 v20, v45, v20
	v_add_f32_e32 v20, v46, v20
	v_pk_mul_f32 v[48:49], v[36:37], v[36:37]
	v_add_f32_e32 v20, v47, v20
	v_add_f32_e32 v20, v48, v20
	v_pk_mul_f32 v[16:17], v[26:27], v[26:27]
	v_add_f32_e32 v20, v49, v20
	v_add_f32_e32 v17, v17, v20
	v_add_f32_e32 v16, v16, v17
	ds_bpermute_b32 v17, v8, v16
	s_waitcnt lgkmcnt(0)
	v_add_f32_e32 v16, v16, v17
	ds_bpermute_b32 v17, v9, v16
	s_waitcnt lgkmcnt(0)
	v_add_f32_e32 v16, v16, v17
	ds_bpermute_b32 v17, v10, v16
	s_waitcnt lgkmcnt(0)
	v_add_f32_e32 v16, v16, v17
	ds_bpermute_b32 v17, v11, v16
	s_waitcnt lgkmcnt(0)
	v_add_f32_e32 v16, v16, v17
	ds_bpermute_b32 v17, v12, v16
	s_waitcnt lgkmcnt(0)
	v_add_f32_e32 v16, v16, v17
	ds_bpermute_b32 v17, v13, v16
	s_waitcnt lgkmcnt(0)
	v_add_f32_e32 v16, v16, v17
	v_fmamk_f32 v16, v16, 0x3a800000, v175
	v_mul_f32_e32 v17, 0x4f800000, v16
	v_cmp_gt_f32_e32 vcc, s33, v16
	s_nop 1
	v_cndmask_b32_e32 v16, v16, v17, vcc
	v_sqrt_f32_e32 v17, v16
	s_nop 0
	v_add_u32_e32 v20, -1, v17
	v_add_u32_e32 v21, 1, v17
	v_fma_f32 v38, -v20, v17, v16
	v_fma_f32 v39, -v21, v17, v16
	v_cmp_ge_f32_e64 s[40:41], 0, v38
	s_nop 1
	v_cndmask_b32_e64 v17, v17, v20, s[40:41]
	v_cmp_lt_f32_e64 s[40:41], 0, v39
	s_nop 1
	v_cndmask_b32_e64 v17, v17, v21, s[40:41]
	v_mul_f32_e32 v20, 0x37800000, v17
	v_cndmask_b32_e32 v17, v17, v20, vcc
	v_cmp_class_f32_e32 vcc, v16, v180
	s_nop 1
	v_cndmask_b32_e32 v16, v17, v16, vcc
	v_div_scale_f32 v17, s[10:11], v16, v16, 1.0
	v_rcp_f32_e32 v21, v17
	v_div_scale_f32 v20, vcc, 1.0, v16, 1.0
	v_fma_f32 v38, -v17, v21, 1.0
	v_fmac_f32_e32 v21, v38, v21
	v_mul_f32_e32 v38, v20, v21
	v_fma_f32 v39, -v17, v38, v20
	v_fmac_f32_e32 v38, v39, v21
	v_fma_f32 v17, -v17, v38, v20
	v_div_fmas_f32 v17, v17, v21, v38
	v_div_fixup_f32 v20, v17, v16, 1.0
	v_pk_mul_f32 v[28:29], v[20:21], v[28:29] op_sel_hi:[0,1]
	v_pk_mul_f32 v[14:15], v[20:21], v[14:15] op_sel_hi:[0,1]
	v_pk_mul_f32 v[16:17], v[24:25], v[14:15]
	v_pk_mul_f32 v[14:15], v[22:23], v[28:29]
	global_store_dwordx4 v[6:7], v[14:17], off
	s_nop 1
	v_mov_b32_e32 v14, v192
	v_mov_b32_e32 v15, v193
	v_mov_b32_e32 v16, v194
	v_mov_b32_e32 v17, v195
	v_pk_mul_f32 v[22:23], v[20:21], v[32:33] op_sel_hi:[0,1]
	v_pk_mul_f32 v[24:25], v[20:21], v[30:31] op_sel_hi:[0,1]
	v_pk_mul_f32 v[18:19], v[20:21], v[18:19] op_sel_hi:[0,1]
	v_cmp_lt_i32_e32 vcc, s67, v3
	s_or_b64 s[42:43], vcc, s[42:43]
	v_pk_mul_f32 v[14:15], v[14:15], v[24:25]
	v_pk_mul_f32 v[16:17], v[16:17], v[22:23]
	global_store_dwordx4 v[6:7], v[14:17], off offset:16
	s_nop 1
	v_mov_b32_e32 v14, v196
	v_mov_b32_e32 v15, v197
	v_mov_b32_e32 v16, v198
	v_mov_b32_e32 v17, v199
	v_pk_mul_f32 v[22:23], v[20:21], v[34:35] op_sel_hi:[0,1]
	v_pk_mul_f32 v[14:15], v[14:15], v[22:23]
	v_pk_mul_f32 v[16:17], v[16:17], v[18:19]
	global_store_dwordx4 v[6:7], v[14:17], off offset:2048
	s_nop 1
	v_mov_b32_e32 v14, v200
	v_mov_b32_e32 v15, v201
	v_mov_b32_e32 v16, v202
	v_mov_b32_e32 v17, v203
	v_pk_mul_f32 v[18:19], v[20:21], v[36:37] op_sel_hi:[0,1]
	v_pk_mul_f32 v[20:21], v[20:21], v[26:27] op_sel_hi:[0,1]
	v_pk_mul_f32 v[14:15], v[14:15], v[18:19]
	v_pk_mul_f32 v[16:17], v[16:17], v[20:21] op_sel:[0,1] op_sel_hi:[1,0]
	global_store_dwordx4 v[6:7], v[14:17], off offset:2064
	v_lshl_add_u64 v[6:7], v[6:7], 0, s[38:39]
	s_andn2_b64 exec, exec, s[42:43]
	s_cbranch_execnz .LBB0_547
